# diagonal-tile causal mask in cmp and slc loops: one compare against an inline constant plus one select per score element
# speedup vs baseline: 1.0044x; 1.0044x over previous
; #define LAS __attribute__((address_space(3)))
; DI int crow(int reg, int hi) { return (reg & 3) + 8 * (reg >> 2) + 4 * hi; }
; #define MFMA32(a, b, c) __builtin_amdgcn_mfma_f32_32x32x16_bf16((a), (b), (c), 0, 0, 0)
; template <bool CMP> DI void tile_compute(LAS unsigned char* lds, int buf, const bf16x8 (&q)[4], int lo, int hv, ASt& st, f32x16& imp0, f32x16& imp1, int jt, LAS float* wsf, int lane) {
;     ...
;     f32x16 p0 = {}, p1 = {};
; #pragma unroll
;     for (int s = 0; s < 4; ++s) { const LAS unsigned char* kb = kb0 + ((r ^ (4 * s + 2 * hi)) * 16);
;         const bf16x8 a0 = *(const LAS bf16x8*)(kb + s * 2048), a1 = *(const LAS bf16x8*)(kb + s * 2048 + 512);
;         p0 = MFMA32(a0, q[s], p0); p1 = MFMA32(a1, q[s], p1); }
;     const bool dead = lo > hv;
;     const bool part = !dead && (lo > 0 || hv < 63);
;     const bool anyPart = __builtin_amdgcn_ballot_w64(part) != 0ull;
;     if (anyPart) {
; #pragma unroll
;         for (int rg = 0; rg < 16; ++rg) { const int k0 = crow(rg, hi), k1 = k0 + 32;
;             p0[rg] = (k0 >= lo && k0 <= hv) ? p0[rg] : NEGB; p1[rg] = (k1 >= lo && k1 <= hv) ? p1[rg] : NEGB; }
;     }
; DI void nsa_unit(const Ctx& c0, int b, int g, int i, LAS unsigned char* lds) {
;     ...
;             int hv = jmax - 64 * k; hv = hv > 63 ? 63 : hv; const int lo = hv < 0 ? 64 : 0;
.LBB0_549:
	v_add_u32_e32 v242, s90, v137
	v_add_u32_e32 v72, v242, v139
	ds_read_b128 v[68:71], v72
	ds_read_b128 v[72:75], v72 offset:512
	v_add_u32_e32 v141, v242, v143
	ds_read_b128 v[234:237], v141 offset:2048
	ds_read_b128 v[238:241], v141 offset:2560
	v_add_u32_e32 v141, v242, v146
	s_waitcnt lgkmcnt(0)
	v_mfma_f32_32x32x16_bf16 v[84:99], v[68:71], v[112:115], 0
	v_cmp_gt_i32_e64 s[82:83], 63, v231
	v_mfma_f32_32x32x16_bf16 v[68:83], v[72:75], v[112:115], 0
	v_mfma_f32_32x32x16_bf16 v[84:99], v[234:237], v[100:103], v[84:99]
	v_mfma_f32_32x32x16_bf16 v[68:83], v[238:241], v[100:103], v[68:83]
	ds_read_b128 v[234:237], v141 offset:4096
	ds_read_b128 v[238:241], v141 offset:4608
	v_min_i32_e32 v141, 63, v231
	s_waitcnt lgkmcnt(0)
	v_mfma_f32_32x32x16_bf16 v[84:99], v[234:237], v[108:111], v[84:99]
	v_add_u32_e32 v235, v242, v147
	ds_read_b128 v[242:245], v235 offset:6144
	v_lshrrev_b32_e32 v234, 25, v231
	v_and_b32_e32 v234, 64, v234
	v_cmp_le_i32_e32 vcc, v234, v141
	v_cmp_gt_i32_e64 s[78:79], v234, v141
	v_mfma_f32_32x32x16_bf16 v[68:83], v[238:241], v[108:111], v[68:83]
	ds_read_b128 v[236:239], v235 offset:6656
	v_and_b32_e32 v235, 0x80000000, v231
	v_cmp_ne_u32_e64 s[80:81], 0, v235
	s_or_b64 s[12:13], s[82:83], s[80:81]
	s_and_b64 s[12:13], s[12:13], vcc
	v_cndmask_b32_e64 v235, 0, 1, s[12:13]
	v_cmp_ne_u32_e32 vcc, 0, v235
	s_waitcnt lgkmcnt(0)
	v_mfma_f32_32x32x16_bf16 v[84:99], v[242:245], v[104:107], v[84:99]
	s_cmp_eq_u64 vcc, 0
	s_cselect_b64 s[12:13], -1, 0
	v_mfma_f32_32x32x16_bf16 v[68:83], v[236:239], v[104:107], v[68:83]
	s_cbranch_vccz .LBB0_551
	v_sub_u32_e32 v249, v141, v148
	v_sub_u32_e32 v249, v249, v234
	v_cmp_gt_i32_e32 vcc, 0, v249
	v_cmp_gt_i32_e64 s[80:81], 32, v249
	s_nop 7
	v_cndmask_b32_e32 v84, v84, v222, vcc
	v_cmp_gt_i32_e32 vcc, 1, v249
	v_cndmask_b32_e64 v68, v68, v222, s[80:81]
	v_cmp_gt_i32_e64 s[80:81], 33, v249
	v_cndmask_b32_e32 v85, v85, v222, vcc
	v_cmp_gt_i32_e32 vcc, 2, v249
	v_cndmask_b32_e64 v69, v69, v222, s[80:81]
	v_cmp_gt_i32_e64 s[80:81], 34, v249
	v_cndmask_b32_e32 v86, v86, v222, vcc
	v_cmp_gt_i32_e32 vcc, 3, v249
	v_cndmask_b32_e64 v70, v70, v222, s[80:81]
	v_cmp_gt_i32_e64 s[80:81], 35, v249
	v_cndmask_b32_e32 v87, v87, v222, vcc
	v_cmp_gt_i32_e32 vcc, 8, v249
	v_cndmask_b32_e64 v71, v71, v222, s[80:81]
	v_cmp_gt_i32_e64 s[80:81], 40, v249
	v_cndmask_b32_e32 v88, v88, v222, vcc
	v_cmp_gt_i32_e32 vcc, 9, v249
	v_cndmask_b32_e64 v72, v72, v222, s[80:81]
	v_cmp_gt_i32_e64 s[80:81], 41, v249
	v_cndmask_b32_e32 v89, v89, v222, vcc
	v_cmp_gt_i32_e32 vcc, 10, v249
	v_cndmask_b32_e64 v73, v73, v222, s[80:81]
	v_cmp_gt_i32_e64 s[80:81], 42, v249
	v_cndmask_b32_e32 v90, v90, v222, vcc
	v_cmp_gt_i32_e32 vcc, 11, v249
	v_cndmask_b32_e64 v74, v74, v222, s[80:81]
	v_cmp_gt_i32_e64 s[80:81], 43, v249
	v_cndmask_b32_e32 v91, v91, v222, vcc
	v_cmp_gt_i32_e32 vcc, 16, v249
	v_cndmask_b32_e64 v75, v75, v222, s[80:81]
	v_cmp_gt_i32_e64 s[80:81], 48, v249
	v_cndmask_b32_e32 v92, v92, v222, vcc
	v_cmp_gt_i32_e32 vcc, 17, v249
	v_cndmask_b32_e64 v76, v76, v222, s[80:81]
	v_cmp_gt_i32_e64 s[80:81], 49, v249
	v_cndmask_b32_e32 v93, v93, v222, vcc
	v_cmp_gt_i32_e32 vcc, 18, v249
	v_cndmask_b32_e64 v77, v77, v222, s[80:81]
	v_cmp_gt_i32_e64 s[80:81], 50, v249
	v_cndmask_b32_e32 v94, v94, v222, vcc
	v_cmp_gt_i32_e32 vcc, 19, v249
	v_cndmask_b32_e64 v78, v78, v222, s[80:81]
	v_cmp_gt_i32_e64 s[80:81], 51, v249
	v_cndmask_b32_e32 v95, v95, v222, vcc
	v_cmp_gt_i32_e32 vcc, 24, v249
	v_cndmask_b32_e64 v79, v79, v222, s[80:81]
	v_cmp_gt_i32_e64 s[80:81], 56, v249
	v_cndmask_b32_e32 v96, v96, v222, vcc
	v_cmp_gt_i32_e32 vcc, 25, v249
	v_cndmask_b32_e64 v80, v80, v222, s[80:81]
	v_cmp_gt_i32_e64 s[80:81], 57, v249
	v_cndmask_b32_e32 v97, v97, v222, vcc
	v_cmp_gt_i32_e32 vcc, 26, v249
	v_cndmask_b32_e64 v81, v81, v222, s[80:81]
	v_cmp_gt_i32_e64 s[80:81], 58, v249
	v_cndmask_b32_e32 v98, v98, v222, vcc
	v_cmp_gt_i32_e32 vcc, 27, v249
	v_cndmask_b32_e64 v82, v82, v222, s[80:81]
	v_cmp_gt_i32_e64 s[80:81], 59, v249
	v_cndmask_b32_e32 v99, v99, v222, vcc
	s_nop 0
	v_cndmask_b32_e64 v83, v83, v222, s[80:81]

; #define LAS __attribute__((address_space(3)))
; DI int crow(int reg, int hi) { return (reg & 3) + 8 * (reg >> 2) + 4 * hi; }
; #define MFMA32(a, b, c) __builtin_amdgcn_mfma_f32_32x32x16_bf16((a), (b), (c), 0, 0, 0)
; template <bool CMP> DI void tile_compute(LAS unsigned char* lds, int buf, const bf16x8 (&q)[4], int lo, int hv, ASt& st, f32x16& imp0, f32x16& imp1, int jt, LAS float* wsf, int lane) {
;     ...
;     f32x16 p0 = {}, p1 = {};
; #pragma unroll
;     for (int s = 0; s < 4; ++s) { const LAS unsigned char* kb = kb0 + ((r ^ (4 * s + 2 * hi)) * 16);
;         const bf16x8 a0 = *(const LAS bf16x8*)(kb + s * 2048), a1 = *(const LAS bf16x8*)(kb + s * 2048 + 512);
;         p0 = MFMA32(a0, q[s], p0); p1 = MFMA32(a1, q[s], p1); }
;     const bool dead = lo > hv;
;     const bool part = !dead && (lo > 0 || hv < 63);
;     const bool anyPart = __builtin_amdgcn_ballot_w64(part) != 0ull;
;     if (anyPart) {
; #pragma unroll
;         for (int rg = 0; rg < 16; ++rg) { const int k0 = crow(rg, hi), k1 = k0 + 32;
;             p0[rg] = (k0 >= lo && k0 <= hv) ? p0[rg] : NEGB; p1[rg] = (k1 >= lo && k1 <= hv) ? p1[rg] : NEGB; }
;     }
; DI void nsa_unit(const Ctx& c0, int b, int g, int i, LAS unsigned char* lds) {
;     ...
;             const bool more = rem != 0ull; int nn = 0;
;             if (more) { nn = __builtin_ctzll(rem); rem &= rem - 1ull; tr = tile_fetch(Kg, Vg, 64 * nn, tid); }
;             const bool selb = (mysel >> n) & 1ull;
;             const int lo = selb ? 0 : 64; const int hv = (n == i) ? ql : 63;
.LBB0_570:
	s_or_b64 exec, exec, s[14:15]
	v_lshrrev_b64 v[4:5], s100, v[116:117]
	v_add_u32_e32 v5, s84, v137
	v_add_u32_e32 v6, v5, v139
	s_cmp_eq_u32 s25, s100
	s_cselect_b64 s[80:81], -1, 0
	ds_read_b128 v[66:69], v6
	ds_read_b128 v[50:53], v6 offset:512
	v_add_u32_e32 v6, v5, v143
	v_and_b32_e32 v2, 1, v4
	ds_read_b128 v[12:15], v6 offset:2048
	ds_read_b128 v[108:111], v6 offset:2560
	v_add_u32_e32 v6, v5, v146
	v_add_u32_e32 v5, v5, v147
	ds_read_b128 v[112:115], v6 offset:4096
	ds_read_b128 v[120:123], v6 offset:4608
	v_cmp_eq_u64_e32 vcc, 0, v[2:3]
	v_cndmask_b32_e64 v4, 63, v125, s[80:81]
	v_cmp_ne_u32_e64 s[82:83], 63, v4
	v_cndmask_b32_e64 v2, 0, 64, vcc
	s_waitcnt lgkmcnt(5)
	v_mfma_f32_32x32x16_bf16 v[66:81], v[66:69], v[82:85], 0
	v_cmp_gt_u32_e64 s[80:81], v2, v4
	s_or_b64 s[14:15], s[82:83], vcc
	s_xor_b64 vcc, s[14:15], s[80:81]
	s_waitcnt lgkmcnt(4)
	v_mfma_f32_32x32x16_bf16 v[50:65], v[50:53], v[82:85], 0
	s_waitcnt lgkmcnt(3)
	v_mfma_f32_32x32x16_bf16 v[66:81], v[12:15], v[90:93], v[66:81]
	ds_read_b128 v[12:15], v5 offset:6144
	s_waitcnt lgkmcnt(3)
	v_mfma_f32_32x32x16_bf16 v[50:65], v[108:111], v[90:93], v[50:65]
	ds_read_b128 v[108:111], v5 offset:6656
	v_cndmask_b32_e64 v5, 0, 1, vcc
	v_cmp_ne_u32_e64 s[82:83], 0, v5
	s_cmp_eq_u64 s[82:83], 0
	s_cselect_b64 s[14:15], -1, 0
	s_waitcnt lgkmcnt(3)
	v_mfma_f32_32x32x16_bf16 v[66:81], v[112:115], v[86:89], v[66:81]
	s_waitcnt lgkmcnt(2)
	v_mfma_f32_32x32x16_bf16 v[50:65], v[120:123], v[86:89], v[50:65]
	s_waitcnt lgkmcnt(1)
	v_mfma_f32_32x32x16_bf16 v[66:81], v[12:15], v[94:97], v[66:81]
	s_waitcnt lgkmcnt(0)
	v_mfma_f32_32x32x16_bf16 v[50:65], v[108:111], v[94:97], v[50:65]
	s_cbranch_vccz .LBB0_572
	v_sub_u32_e32 v249, v4, v148
	v_sub_u32_e32 v249, v249, v2
	v_cmp_gt_i32_e32 vcc, 0, v249
	v_cmp_gt_i32_e64 s[82:83], 32, v249
	s_nop 7
	v_cndmask_b32_e32 v66, v66, v222, vcc
	v_cmp_gt_i32_e32 vcc, 1, v249
	v_cndmask_b32_e64 v50, v50, v222, s[82:83]
	v_cmp_gt_i32_e64 s[82:83], 33, v249
	v_cndmask_b32_e32 v67, v67, v222, vcc
	v_cmp_gt_i32_e32 vcc, 2, v249
	v_cndmask_b32_e64 v51, v51, v222, s[82:83]
	v_cmp_gt_i32_e64 s[82:83], 34, v249
	v_cndmask_b32_e32 v68, v68, v222, vcc
	v_cmp_gt_i32_e32 vcc, 3, v249
	v_cndmask_b32_e64 v52, v52, v222, s[82:83]
	v_cmp_gt_i32_e64 s[82:83], 35, v249
	v_cndmask_b32_e32 v69, v69, v222, vcc
	v_cmp_gt_i32_e32 vcc, 8, v249
	v_cndmask_b32_e64 v53, v53, v222, s[82:83]
	v_cmp_gt_i32_e64 s[82:83], 40, v249
	v_cndmask_b32_e32 v70, v70, v222, vcc
	v_cmp_gt_i32_e32 vcc, 9, v249
	v_cndmask_b32_e64 v54, v54, v222, s[82:83]
	v_cmp_gt_i32_e64 s[82:83], 41, v249
	v_cndmask_b32_e32 v71, v71, v222, vcc
	v_cmp_gt_i32_e32 vcc, 10, v249
	v_cndmask_b32_e64 v55, v55, v222, s[82:83]
	v_cmp_gt_i32_e64 s[82:83], 42, v249
	v_cndmask_b32_e32 v72, v72, v222, vcc
	v_cmp_gt_i32_e32 vcc, 11, v249
	v_cndmask_b32_e64 v56, v56, v222, s[82:83]
	v_cmp_gt_i32_e64 s[82:83], 43, v249
	v_cndmask_b32_e32 v73, v73, v222, vcc
	v_cmp_gt_i32_e32 vcc, 16, v249
	v_cndmask_b32_e64 v57, v57, v222, s[82:83]
	v_cmp_gt_i32_e64 s[82:83], 48, v249
	v_cndmask_b32_e32 v74, v74, v222, vcc
	v_cmp_gt_i32_e32 vcc, 17, v249
	v_cndmask_b32_e64 v58, v58, v222, s[82:83]
	v_cmp_gt_i32_e64 s[82:83], 49, v249
	v_cndmask_b32_e32 v75, v75, v222, vcc
	v_cmp_gt_i32_e32 vcc, 18, v249
	v_cndmask_b32_e64 v59, v59, v222, s[82:83]
	v_cmp_gt_i32_e64 s[82:83], 50, v249
	v_cndmask_b32_e32 v76, v76, v222, vcc
	v_cmp_gt_i32_e32 vcc, 19, v249
	v_cndmask_b32_e64 v60, v60, v222, s[82:83]
	v_cmp_gt_i32_e64 s[82:83], 51, v249
	v_cndmask_b32_e32 v77, v77, v222, vcc
	v_cmp_gt_i32_e32 vcc, 24, v249
	v_cndmask_b32_e64 v61, v61, v222, s[82:83]
	v_cmp_gt_i32_e64 s[82:83], 56, v249
	v_cndmask_b32_e32 v78, v78, v222, vcc
	v_cmp_gt_i32_e32 vcc, 25, v249
	v_cndmask_b32_e64 v62, v62, v222, s[82:83]
	v_cmp_gt_i32_e64 s[82:83], 57, v249
	v_cndmask_b32_e32 v79, v79, v222, vcc
	v_cmp_gt_i32_e32 vcc, 26, v249
	v_cndmask_b32_e64 v63, v63, v222, s[82:83]
	v_cmp_gt_i32_e64 s[82:83], 58, v249
	v_cndmask_b32_e32 v80, v80, v222, vcc
	v_cmp_gt_i32_e32 vcc, 27, v249
	v_cndmask_b32_e64 v64, v64, v222, s[82:83]
	v_cmp_gt_i32_e64 s[82:83], 59, v249
	v_cndmask_b32_e32 v81, v81, v222, vcc
	s_nop 0
	v_cndmask_b32_e64 v65, v65, v222, s[82:83]

; #define LAS __attribute__((address_space(3)))
; DI int crow(int reg, int hi) { return (reg & 3) + 8 * (reg >> 2) + 4 * hi; }
; #define MFMA32(a, b, c) __builtin_amdgcn_mfma_f32_32x32x16_bf16((a), (b), (c), 0, 0, 0)
; template <bool CMP> DI void tile_compute(LAS unsigned char* lds, int buf, const bf16x8 (&q)[4], int lo, int hv, ASt& st, f32x16& imp0, f32x16& imp1, int jt, LAS float* wsf, int lane) {
;     ...
;     f32x16 p0 = {}, p1 = {};
; #pragma unroll
;     for (int s = 0; s < 4; ++s) { const LAS unsigned char* kb = kb0 + ((r ^ (4 * s + 2 * hi)) * 16);
;         const bf16x8 a0 = *(const LAS bf16x8*)(kb + s * 2048), a1 = *(const LAS bf16x8*)(kb + s * 2048 + 512);
;         p0 = MFMA32(a0, q[s], p0); p1 = MFMA32(a1, q[s], p1); }
;     const bool dead = lo > hv;
;     const bool part = !dead && (lo > 0 || hv < 63);
;     const bool anyPart = __builtin_amdgcn_ballot_w64(part) != 0ull;
;     if (anyPart) {
; #pragma unroll
;         for (int rg = 0; rg < 16; ++rg) { const int k0 = crow(rg, hi), k1 = k0 + 32;
;             p0[rg] = (k0 >= lo && k0 <= hv) ? p0[rg] : NEGB; p1[rg] = (k1 >= lo && k1 <= hv) ? p1[rg] : NEGB; }
;     }
; DI void nsa_unit(const Ctx& c0, int b, int g, int i, LAS unsigned char* lds) {
;     ...
;             int hv = jmax - 64 * k; hv = hv > 63 ? 63 : hv; const int lo = hv < 0 ? 64 : 0;
.LBB0_1162:
	v_add_u32_e32 v229, s28, v137
	v_add_u32_e32 v72, v229, v139
	ds_read_b128 v[68:71], v72
	ds_read_b128 v[72:75], v72 offset:512
	v_add_u32_e32 v141, v229, v143
	ds_read_b128 v[230:233], v141 offset:2048
	ds_read_b128 v[234:237], v141 offset:2560
	v_add_u32_e32 v141, v229, v146
	s_waitcnt lgkmcnt(0)
	v_mfma_f32_32x32x16_bf16 v[84:99], v[68:71], v[112:115], 0
	v_add_u32_e32 v238, v229, v147
	v_lshrrev_b32_e32 v229, 25, v226
	v_and_b32_e32 v229, 64, v229
	v_cmp_gt_i32_e64 s[86:87], 63, v226
	v_mfma_f32_32x32x16_bf16 v[68:83], v[72:75], v[112:115], 0
	v_mfma_f32_32x32x16_bf16 v[84:99], v[230:233], v[100:103], v[84:99]
	v_mfma_f32_32x32x16_bf16 v[68:83], v[234:237], v[100:103], v[68:83]
	ds_read_b128 v[230:233], v141 offset:4096
	ds_read_b128 v[234:237], v141 offset:4608
	v_min_i32_e32 v141, 63, v226
	v_cmp_le_i32_e32 vcc, v229, v141
	v_cmp_gt_i32_e64 s[80:81], v229, v141
	s_waitcnt lgkmcnt(0)
	v_mfma_f32_32x32x16_bf16 v[84:99], v[230:233], v[108:111], v[84:99]
	ds_read_b128 v[230:233], v238 offset:6144
	v_mfma_f32_32x32x16_bf16 v[68:83], v[234:237], v[108:111], v[68:83]
	ds_read_b128 v[234:237], v238 offset:6656
	v_and_b32_e32 v238, 0x80000000, v226
	v_cmp_ne_u32_e64 s[82:83], 0, v238
	s_or_b64 s[14:15], s[86:87], s[82:83]
	s_and_b64 s[14:15], s[14:15], vcc
	s_waitcnt lgkmcnt(0)
	v_mfma_f32_32x32x16_bf16 v[84:99], v[230:233], v[104:107], v[84:99]
	v_cndmask_b32_e64 v230, 0, 1, s[14:15]
	v_cmp_ne_u32_e32 vcc, 0, v230
	s_cmp_eq_u64 vcc, 0
	s_cselect_b64 s[14:15], -1, 0
	v_mfma_f32_32x32x16_bf16 v[68:83], v[234:237], v[104:107], v[68:83]
	s_cbranch_vccz .LBB0_1164
	v_sub_u32_e32 v249, v141, v148
	v_sub_u32_e32 v249, v249, v229
	v_cmp_gt_i32_e32 vcc, 0, v249
	v_cmp_gt_i32_e64 s[82:83], 32, v249
	s_nop 7
	v_cndmask_b32_e32 v84, v84, v217, vcc
	v_cmp_gt_i32_e32 vcc, 1, v249
	v_cndmask_b32_e64 v68, v68, v217, s[82:83]
	v_cmp_gt_i32_e64 s[82:83], 33, v249
	v_cndmask_b32_e32 v85, v85, v217, vcc
	v_cmp_gt_i32_e32 vcc, 2, v249
	v_cndmask_b32_e64 v69, v69, v217, s[82:83]
	v_cmp_gt_i32_e64 s[82:83], 34, v249
	v_cndmask_b32_e32 v86, v86, v217, vcc
	v_cmp_gt_i32_e32 vcc, 3, v249
	v_cndmask_b32_e64 v70, v70, v217, s[82:83]
	v_cmp_gt_i32_e64 s[82:83], 35, v249
	v_cndmask_b32_e32 v87, v87, v217, vcc
	v_cmp_gt_i32_e32 vcc, 8, v249
	v_cndmask_b32_e64 v71, v71, v217, s[82:83]
	v_cmp_gt_i32_e64 s[82:83], 40, v249
	v_cndmask_b32_e32 v88, v88, v217, vcc
	v_cmp_gt_i32_e32 vcc, 9, v249
	v_cndmask_b32_e64 v72, v72, v217, s[82:83]
	v_cmp_gt_i32_e64 s[82:83], 41, v249
	v_cndmask_b32_e32 v89, v89, v217, vcc
	v_cmp_gt_i32_e32 vcc, 10, v249
	v_cndmask_b32_e64 v73, v73, v217, s[82:83]
	v_cmp_gt_i32_e64 s[82:83], 42, v249
	v_cndmask_b32_e32 v90, v90, v217, vcc
	v_cmp_gt_i32_e32 vcc, 11, v249
	v_cndmask_b32_e64 v74, v74, v217, s[82:83]
	v_cmp_gt_i32_e64 s[82:83], 43, v249
	v_cndmask_b32_e32 v91, v91, v217, vcc
	v_cmp_gt_i32_e32 vcc, 16, v249
	v_cndmask_b32_e64 v75, v75, v217, s[82:83]
	v_cmp_gt_i32_e64 s[82:83], 48, v249
	v_cndmask_b32_e32 v92, v92, v217, vcc
	v_cmp_gt_i32_e32 vcc, 17, v249
	v_cndmask_b32_e64 v76, v76, v217, s[82:83]
	v_cmp_gt_i32_e64 s[82:83], 49, v249
	v_cndmask_b32_e32 v93, v93, v217, vcc
	v_cmp_gt_i32_e32 vcc, 18, v249
	v_cndmask_b32_e64 v77, v77, v217, s[82:83]
	v_cmp_gt_i32_e64 s[82:83], 50, v249
	v_cndmask_b32_e32 v94, v94, v217, vcc
	v_cmp_gt_i32_e32 vcc, 19, v249
	v_cndmask_b32_e64 v78, v78, v217, s[82:83]
	v_cmp_gt_i32_e64 s[82:83], 51, v249
	v_cndmask_b32_e32 v95, v95, v217, vcc
	v_cmp_gt_i32_e32 vcc, 24, v249
	v_cndmask_b32_e64 v79, v79, v217, s[82:83]
	v_cmp_gt_i32_e64 s[82:83], 56, v249
	v_cndmask_b32_e32 v96, v96, v217, vcc
	v_cmp_gt_i32_e32 vcc, 25, v249
	v_cndmask_b32_e64 v80, v80, v217, s[82:83]
	v_cmp_gt_i32_e64 s[82:83], 57, v249
	v_cndmask_b32_e32 v97, v97, v217, vcc
	v_cmp_gt_i32_e32 vcc, 26, v249
	v_cndmask_b32_e64 v81, v81, v217, s[82:83]
	v_cmp_gt_i32_e64 s[82:83], 58, v249
	v_cndmask_b32_e32 v98, v98, v217, vcc
	v_cmp_gt_i32_e32 vcc, 27, v249
	v_cndmask_b32_e64 v82, v82, v217, s[82:83]
	v_cmp_gt_i32_e64 s[82:83], 59, v249
	v_cndmask_b32_e32 v99, v99, v217, vcc
	s_nop 0
	v_cndmask_b32_e64 v83, v83, v217, s[82:83]

; #define LAS __attribute__((address_space(3)))
; DI int crow(int reg, int hi) { return (reg & 3) + 8 * (reg >> 2) + 4 * hi; }
; #define MFMA32(a, b, c) __builtin_amdgcn_mfma_f32_32x32x16_bf16((a), (b), (c), 0, 0, 0)
; template <bool CMP> DI void tile_compute(LAS unsigned char* lds, int buf, const bf16x8 (&q)[4], int lo, int hv, ASt& st, f32x16& imp0, f32x16& imp1, int jt, LAS float* wsf, int lane) {
;     ...
;     f32x16 p0 = {}, p1 = {};
; #pragma unroll
;     for (int s = 0; s < 4; ++s) { const LAS unsigned char* kb = kb0 + ((r ^ (4 * s + 2 * hi)) * 16);
;         const bf16x8 a0 = *(const LAS bf16x8*)(kb + s * 2048), a1 = *(const LAS bf16x8*)(kb + s * 2048 + 512);
;         p0 = MFMA32(a0, q[s], p0); p1 = MFMA32(a1, q[s], p1); }
;     const bool dead = lo > hv;
;     const bool part = !dead && (lo > 0 || hv < 63);
;     const bool anyPart = __builtin_amdgcn_ballot_w64(part) != 0ull;
;     if (anyPart) {
; #pragma unroll
;         for (int rg = 0; rg < 16; ++rg) { const int k0 = crow(rg, hi), k1 = k0 + 32;
;             p0[rg] = (k0 >= lo && k0 <= hv) ? p0[rg] : NEGB; p1[rg] = (k1 >= lo && k1 <= hv) ? p1[rg] : NEGB; }
;     }
; DI void nsa_unit(const Ctx& c0, int b, int g, int i, LAS unsigned char* lds) {
;     ...
;             const bool more = rem != 0ull; int nn = 0;
;             if (more) { nn = __builtin_ctzll(rem); rem &= rem - 1ull; tr = tile_fetch(Kg, Vg, 64 * nn, tid); }
;             const bool selb = (mysel >> n) & 1ull;
;             const int lo = selb ? 0 : 64; const int hv = (n == i) ? ql : 63;
.LBB0_1183:
	s_or_b64 exec, exec, s[16:17]
	v_lshrrev_b64 v[4:5], s100, v[116:117]
	v_add_u32_e32 v5, s28, v137
	v_add_u32_e32 v6, v5, v139
	s_cmp_eq_u32 s27, s100
	s_cselect_b64 s[82:83], -1, 0
	ds_read_b128 v[66:69], v6
	ds_read_b128 v[50:53], v6 offset:512
	v_add_u32_e32 v6, v5, v143
	v_and_b32_e32 v2, 1, v4
	ds_read_b128 v[12:15], v6 offset:2048
	ds_read_b128 v[108:111], v6 offset:2560
	v_add_u32_e32 v6, v5, v146
	v_add_u32_e32 v5, v5, v147
	ds_read_b128 v[112:115], v6 offset:4096
	ds_read_b128 v[120:123], v6 offset:4608
	v_cmp_eq_u64_e32 vcc, 0, v[2:3]
	v_cndmask_b32_e64 v4, 63, v125, s[82:83]
	v_cmp_ne_u32_e64 s[86:87], 63, v4
	v_cndmask_b32_e64 v2, 0, 64, vcc
	s_waitcnt lgkmcnt(5)
	v_mfma_f32_32x32x16_bf16 v[66:81], v[66:69], v[82:85], 0
	v_cmp_gt_u32_e64 s[82:83], v2, v4
	s_or_b64 s[16:17], s[86:87], vcc
	s_xor_b64 vcc, s[16:17], s[82:83]
	s_waitcnt lgkmcnt(4)
	v_mfma_f32_32x32x16_bf16 v[50:65], v[50:53], v[82:85], 0
	s_waitcnt lgkmcnt(3)
	v_mfma_f32_32x32x16_bf16 v[66:81], v[12:15], v[90:93], v[66:81]
	ds_read_b128 v[12:15], v5 offset:6144
	s_waitcnt lgkmcnt(3)
	v_mfma_f32_32x32x16_bf16 v[50:65], v[108:111], v[90:93], v[50:65]
	ds_read_b128 v[108:111], v5 offset:6656
	v_cndmask_b32_e64 v5, 0, 1, vcc
	v_cmp_ne_u32_e64 s[86:87], 0, v5
	s_cmp_eq_u64 s[86:87], 0
	s_cselect_b64 s[16:17], -1, 0
	s_waitcnt lgkmcnt(3)
	v_mfma_f32_32x32x16_bf16 v[66:81], v[112:115], v[86:89], v[66:81]
	s_waitcnt lgkmcnt(2)
	v_mfma_f32_32x32x16_bf16 v[50:65], v[120:123], v[86:89], v[50:65]
	s_waitcnt lgkmcnt(1)
	v_mfma_f32_32x32x16_bf16 v[66:81], v[12:15], v[94:97], v[66:81]
	s_waitcnt lgkmcnt(0)
	v_mfma_f32_32x32x16_bf16 v[50:65], v[108:111], v[94:97], v[50:65]
	s_cbranch_vccz .LBB0_1185
	v_sub_u32_e32 v249, v4, v148
	v_sub_u32_e32 v249, v249, v2
	v_cmp_gt_i32_e32 vcc, 0, v249
	v_cmp_gt_i32_e64 s[86:87], 32, v249
	s_nop 7
	v_cndmask_b32_e32 v66, v66, v217, vcc
	v_cmp_gt_i32_e32 vcc, 1, v249
	v_cndmask_b32_e64 v50, v50, v217, s[86:87]
	v_cmp_gt_i32_e64 s[86:87], 33, v249
	v_cndmask_b32_e32 v67, v67, v217, vcc
	v_cmp_gt_i32_e32 vcc, 2, v249
	v_cndmask_b32_e64 v51, v51, v217, s[86:87]
	v_cmp_gt_i32_e64 s[86:87], 34, v249
	v_cndmask_b32_e32 v68, v68, v217, vcc
	v_cmp_gt_i32_e32 vcc, 3, v249
	v_cndmask_b32_e64 v52, v52, v217, s[86:87]
	v_cmp_gt_i32_e64 s[86:87], 35, v249
	v_cndmask_b32_e32 v69, v69, v217, vcc
	v_cmp_gt_i32_e32 vcc, 8, v249
	v_cndmask_b32_e64 v53, v53, v217, s[86:87]
	v_cmp_gt_i32_e64 s[86:87], 40, v249
	v_cndmask_b32_e32 v70, v70, v217, vcc
	v_cmp_gt_i32_e32 vcc, 9, v249
	v_cndmask_b32_e64 v54, v54, v217, s[86:87]
	v_cmp_gt_i32_e64 s[86:87], 41, v249
	v_cndmask_b32_e32 v71, v71, v217, vcc
	v_cmp_gt_i32_e32 vcc, 10, v249
	v_cndmask_b32_e64 v55, v55, v217, s[86:87]
	v_cmp_gt_i32_e64 s[86:87], 42, v249
	v_cndmask_b32_e32 v72, v72, v217, vcc
	v_cmp_gt_i32_e32 vcc, 11, v249
	v_cndmask_b32_e64 v56, v56, v217, s[86:87]
	v_cmp_gt_i32_e64 s[86:87], 43, v249
	v_cndmask_b32_e32 v73, v73, v217, vcc
	v_cmp_gt_i32_e32 vcc, 16, v249
	v_cndmask_b32_e64 v57, v57, v217, s[86:87]
	v_cmp_gt_i32_e64 s[86:87], 48, v249
	v_cndmask_b32_e32 v74, v74, v217, vcc
	v_cmp_gt_i32_e32 vcc, 17, v249
	v_cndmask_b32_e64 v58, v58, v217, s[86:87]
	v_cmp_gt_i32_e64 s[86:87], 49, v249
	v_cndmask_b32_e32 v75, v75, v217, vcc
	v_cmp_gt_i32_e32 vcc, 18, v249
	v_cndmask_b32_e64 v59, v59, v217, s[86:87]
	v_cmp_gt_i32_e64 s[86:87], 50, v249
	v_cndmask_b32_e32 v76, v76, v217, vcc
	v_cmp_gt_i32_e32 vcc, 19, v249
	v_cndmask_b32_e64 v60, v60, v217, s[86:87]
	v_cmp_gt_i32_e64 s[86:87], 51, v249
	v_cndmask_b32_e32 v77, v77, v217, vcc
	v_cmp_gt_i32_e32 vcc, 24, v249
	v_cndmask_b32_e64 v61, v61, v217, s[86:87]
	v_cmp_gt_i32_e64 s[86:87], 56, v249
	v_cndmask_b32_e32 v78, v78, v217, vcc
	v_cmp_gt_i32_e32 vcc, 25, v249
	v_cndmask_b32_e64 v62, v62, v217, s[86:87]
	v_cmp_gt_i32_e64 s[86:87], 57, v249
	v_cndmask_b32_e32 v79, v79, v217, vcc
	v_cmp_gt_i32_e32 vcc, 26, v249
	v_cndmask_b32_e64 v63, v63, v217, s[86:87]
	v_cmp_gt_i32_e64 s[86:87], 58, v249
	v_cndmask_b32_e32 v80, v80, v217, vcc
	v_cmp_gt_i32_e32 vcc, 27, v249
	v_cndmask_b32_e64 v64, v64, v217, s[86:87]
	v_cmp_gt_i32_e64 s[86:87], 59, v249
	v_cndmask_b32_e32 v81, v81, v217, vcc
	s_nop 0
	v_cndmask_b32_e64 v65, v65, v217, s[86:87]
